# cand2 + trailing-half barrier elision: last post-MFMA barrier of each proj/ffn_in unit only on the leading half
# baseline (speedup 1.0000x reference)
; #define PG8_STAGE(bufoff, gbase, voff) do { const char* gb_ = (const char*)(gbase); asm volatile("" : "+s"(gb_)); _Pragma("unroll") for (int _i = 0; _i < 2; ++_i) { unsigned vo_ = (voff)[_i]; asm volatile("" : "+v"(vo_));        \
;         __builtin_amdgcn_global_load_lds((const unsigned*)(gb_ + vo_), (PG8_LAS unsigned*)(lds + (bufoff) + ldsw + _i * 8192), 16, 0, 0); } } while (0)
; #define PG8_LDA(dst, b, h) do { _Pragma("unroll") for (int m = 0; m < 4; ++m) _Pragma("unroll") for (int k = 0; k < 2; ++k) dst[m][k] = *(const PG8_LAS bf16x8*)(lds + PG8_SA(b, h) + aoff + m * 2048 + k * 1024); } while (0)
; #define PG8_LDB(dst, b, h) do { _Pragma("unroll") for (int n = 0; n < 2; ++n) _Pragma("unroll") for (int k = 0; k < 2; ++k) dst[n][k] = *(const PG8_LAS bf16x8*)(lds + PG8_SB(b, h) + boff + n * 2048 + k * 1024); } while (0)
; #define PG8_MMA(ai, bj, At, Bt) do { __builtin_amdgcn_s_setprio(1); _Pragma("unroll") for (int m = 0; m < 4; ++m) _Pragma("unroll") for (int n = 0; n < 2; ++n) _Pragma("unroll") for (int k = 0; k < 2; ++k) \
;         acc[ai][bj][m][n] = __builtin_amdgcn_mfma_f32_16x16x32_bf16(Bt[n][k], At[m][k], acc[ai][bj][m][n], 0, 0, 0); __builtin_amdgcn_s_setprio(0); } while (0)
; #define PG8_WAIT_V(n) asm volatile("s_waitcnt vmcnt(" #n ")" ::: "memory")
; template <class Epi, class Sched, bool ALIGN_EPI = false, bool SP2 = false>
; __device__ __forceinline__ void gemm_phase(PG8_LAS unsigned char* lds, const Gemm g, const Sched& S, const Epi& E) {
;     ...
;             const bool last = (t == nt - 2);
;             const char* a1 = cA + (size_t)(t + 1) * kstep;
;             const char* a2 = last ? nA : cA + (size_t)(t + 2) * kstep; const char* b2 = last ? nB : cB + (size_t)(t + 2) * kstep;
;             const char* a3 = a2 + kstep; const char* b3 = b2 + kstep;
;             if (last && has_next) S.a_ready(nxt);
;             if constexpr (SP2) {
;             PG8_LDB(B0, 0, 0); PG8_LDB(B1, 0, 1); PG8_SCHED; PG8_LDA(At, 0, 0); PG8_STAGE(PG8_SA(1, 1), a1 + hstep, voffA);
;             PG8_WAIT_V(8); PG8_WAIT_L(0); PG8_BAR; PG8_MMA(0, 0, At, B0); PG8_MMA(0, 1, At, B1); PG8_BAR; PG8_SCHED;
;             PG8_LDA(At, 0, 1); PG8_STAGE(PG8_SB(0, 0), b2, voffB); PG8_STAGE(PG8_SB(0, 1), b2 + hstep, voffB); PG8_STAGE(PG8_SA(0, 0), a2, voffA);
;             PG8_WAIT_V(8); PG8_WAIT_L(0); PG8_BAR; PG8_MMA(1, 0, At, B0); PG8_MMA(1, 1, At, B1); PG8_BAR; PG8_SCHED;
.LBB0_232:
	s_add_u32 s2, s0, 0x100
	s_addc_u32 s3, s1, 0
	s_cmp_eq_u32 s30, 28
	s_cselect_b32 s10, s25, s2
	s_cselect_b32 s11, s24, s3
	s_cselect_b32 s8, s27, s28
	s_cselect_b32 s9, s26, s29
	s_add_u32 s6, s10, 0x80
	s_addc_u32 s7, s11, 0
	s_add_i32 s31, 0, 0x10000
	s_add_i32 s33, 0, 0x14000
	ds_read_b128 v[66:69], v244
	ds_read_b128 v[70:73], v244 offset:1024
	ds_read_b128 v[74:77], v244 offset:2048
	ds_read_b128 v[78:81], v244 offset:3072
	ds_read_b128 v[146:149], v244 offset:16384
	ds_read_b128 v[150:153], v244 offset:17408
	ds_read_b128 v[154:157], v244 offset:18432
	ds_read_b128 v[158:161], v244 offset:19456
	s_add_u32 s0, s0, 0x80080
	s_addc_u32 s1, s1, 0
	ds_read_b128 v[178:181], v223
	ds_read_b128 v[182:185], v223 offset:1024
	ds_read_b128 v[192:195], v223 offset:2048
	ds_read_b128 v[196:199], v223 offset:3072
	ds_read_b128 v[200:203], v223 offset:4096
	ds_read_b128 v[204:207], v223 offset:5120
	ds_read_b128 v[208:211], v223 offset:6144
	ds_read_b128 v[212:215], v223 offset:7168
	s_add_i32 m0, s13, 0xc000
	s_nop 0
	global_load_lds_dwordx4 v1, s[0:1]
	s_add_i32 m0, s13, 0xe000
	s_nop 0
	global_load_lds_dwordx4 v191, s[0:1]
	s_waitcnt vmcnt(8)
	s_waitcnt lgkmcnt(0)
	s_barrier
	s_setprio 1
	s_waitcnt lgkmcnt(0)
	v_mfma_f32_16x16x32_bf16 v[142:145], v[66:69], v[178:181], v[142:145]
	v_mfma_f32_16x16x32_bf16 v[142:145], v[70:73], v[182:185], v[142:145]
	v_mfma_f32_16x16x32_bf16 v[134:137], v[66:69], v[192:195], v[134:137]
	v_mfma_f32_16x16x32_bf16 v[134:137], v[70:73], v[196:199], v[134:137]
	v_mfma_f32_16x16x32_bf16 v[126:129], v[66:69], v[200:203], v[126:129]
	v_mfma_f32_16x16x32_bf16 v[126:129], v[70:73], v[204:207], v[126:129]
	v_mfma_f32_16x16x32_bf16 v[118:121], v[66:69], v[208:211], v[118:121]
	v_mfma_f32_16x16x32_bf16 v[118:121], v[70:73], v[212:215], v[118:121]
	v_mfma_f32_16x16x32_bf16 v[138:141], v[74:77], v[178:181], v[138:141]
	v_mfma_f32_16x16x32_bf16 v[138:141], v[78:81], v[182:185], v[138:141]
	v_mfma_f32_16x16x32_bf16 v[130:133], v[74:77], v[192:195], v[130:133]
	v_mfma_f32_16x16x32_bf16 v[130:133], v[78:81], v[196:199], v[130:133]
	v_mfma_f32_16x16x32_bf16 v[122:125], v[74:77], v[200:203], v[122:125]
	v_mfma_f32_16x16x32_bf16 v[122:125], v[78:81], v[204:207], v[122:125]
	v_mfma_f32_16x16x32_bf16 v[114:117], v[74:77], v[208:211], v[114:117]
	v_mfma_f32_16x16x32_bf16 v[114:117], v[78:81], v[212:215], v[114:117]
	s_setprio 0
	s_setprio 1
	v_mfma_f32_16x16x32_bf16 v[62:65], v[146:149], v[178:181], v[62:65]
	v_mfma_f32_16x16x32_bf16 v[62:65], v[150:153], v[182:185], v[62:65]
	v_mfma_f32_16x16x32_bf16 v[54:57], v[146:149], v[192:195], v[54:57]
	v_mfma_f32_16x16x32_bf16 v[54:57], v[150:153], v[196:199], v[54:57]
	v_mfma_f32_16x16x32_bf16 v[46:49], v[146:149], v[200:203], v[46:49]
	v_mfma_f32_16x16x32_bf16 v[46:49], v[150:153], v[204:207], v[46:49]
	v_mfma_f32_16x16x32_bf16 v[38:41], v[146:149], v[208:211], v[38:41]
	v_mfma_f32_16x16x32_bf16 v[38:41], v[150:153], v[212:215], v[38:41]
	v_mfma_f32_16x16x32_bf16 v[58:61], v[154:157], v[178:181], v[58:61]
	v_mfma_f32_16x16x32_bf16 v[58:61], v[158:161], v[182:185], v[58:61]
	v_mfma_f32_16x16x32_bf16 v[50:53], v[154:157], v[192:195], v[50:53]
	v_mfma_f32_16x16x32_bf16 v[50:53], v[158:161], v[196:199], v[50:53]
	v_mfma_f32_16x16x32_bf16 v[42:45], v[154:157], v[200:203], v[42:45]
	v_mfma_f32_16x16x32_bf16 v[42:45], v[158:161], v[204:207], v[42:45]
	v_mfma_f32_16x16x32_bf16 v[34:37], v[154:157], v[208:211], v[34:37]
	v_mfma_f32_16x16x32_bf16 v[34:37], v[158:161], v[212:215], v[34:37]
	s_setprio 0
	s_barrier
	s_mov_b64 s[0:1], s[8:9]
	s_add_i32 s31, s31, s12
	ds_read_b128 v[178:181], v223 offset:16384
	ds_read_b128 v[182:185], v223 offset:17408
	ds_read_b128 v[192:195], v223 offset:18432
	ds_read_b128 v[196:199], v223 offset:19456
	ds_read_b128 v[200:203], v223 offset:20480
	ds_read_b128 v[204:207], v223 offset:21504
	ds_read_b128 v[208:211], v223 offset:22528
	ds_read_b128 v[212:215], v223 offset:23552
	s_mov_b32 m0, s31
	s_nop 0
	global_load_lds_dwordx4 v189, s[0:1]
	s_add_i32 m0, s31, 0x2000
	s_nop 0
	global_load_lds_dwordx4 v219, s[0:1]
	s_add_u32 s0, s8, 0x80000
	s_addc_u32 s1, s9, 0
	s_add_i32 s31, s33, s12
	s_mov_b32 m0, s31
	s_nop 0
	global_load_lds_dwordx4 v189, s[0:1]
	s_add_i32 m0, s31, 0x2000
	s_nop 0
	global_load_lds_dwordx4 v219, s[0:1]
	s_mov_b64 s[0:1], s[10:11]
	s_mov_b32 m0, s13
	s_nop 0
	global_load_lds_dwordx4 v1, s[0:1]
	s_mov_b32 m0, s14
	s_nop 0
	global_load_lds_dwordx4 v191, s[0:1]
	s_waitcnt vmcnt(8)
	s_waitcnt lgkmcnt(0)
	s_barrier
	s_setprio 1
	s_waitcnt lgkmcnt(0)
	v_mfma_f32_16x16x32_bf16 v[110:113], v[66:69], v[178:181], v[110:113]
	v_mfma_f32_16x16x32_bf16 v[110:113], v[70:73], v[182:185], v[110:113]
	v_mfma_f32_16x16x32_bf16 v[102:105], v[66:69], v[192:195], v[102:105]
	v_mfma_f32_16x16x32_bf16 v[102:105], v[70:73], v[196:199], v[102:105]
	v_mfma_f32_16x16x32_bf16 v[94:97], v[66:69], v[200:203], v[94:97]
	v_mfma_f32_16x16x32_bf16 v[94:97], v[70:73], v[204:207], v[94:97]
	v_mfma_f32_16x16x32_bf16 v[66:69], v[66:69], v[208:211], v[86:89]
	v_mfma_f32_16x16x32_bf16 v[66:69], v[70:73], v[212:215], v[66:69]
	v_mfma_f32_16x16x32_bf16 v[106:109], v[74:77], v[178:181], v[106:109]
	v_mfma_f32_16x16x32_bf16 v[106:109], v[78:81], v[182:185], v[106:109]
	v_mfma_f32_16x16x32_bf16 v[98:101], v[74:77], v[192:195], v[98:101]
	v_mfma_f32_16x16x32_bf16 v[98:101], v[78:81], v[196:199], v[98:101]
	v_mfma_f32_16x16x32_bf16 v[90:93], v[74:77], v[200:203], v[90:93]
	v_mfma_f32_16x16x32_bf16 v[90:93], v[78:81], v[204:207], v[90:93]
	v_mfma_f32_16x16x32_bf16 v[70:73], v[74:77], v[208:211], v[82:85]
	v_mfma_f32_16x16x32_bf16 v[70:73], v[78:81], v[212:215], v[70:73]
	s_setprio 0
	s_setprio 1
	v_mfma_f32_16x16x32_bf16 v[30:33], v[146:149], v[178:181], v[30:33]
	v_mfma_f32_16x16x32_bf16 v[30:33], v[150:153], v[182:185], v[30:33]
	v_mfma_f32_16x16x32_bf16 v[22:25], v[146:149], v[192:195], v[22:25]
	v_mfma_f32_16x16x32_bf16 v[22:25], v[150:153], v[196:199], v[22:25]
	v_mfma_f32_16x16x32_bf16 v[14:17], v[146:149], v[200:203], v[14:17]
	v_mfma_f32_16x16x32_bf16 v[14:17], v[150:153], v[204:207], v[14:17]
	v_mfma_f32_16x16x32_bf16 v[6:9], v[146:149], v[208:211], v[6:9]
	v_mfma_f32_16x16x32_bf16 v[6:9], v[150:153], v[212:215], v[6:9]
	v_mfma_f32_16x16x32_bf16 v[26:29], v[154:157], v[178:181], v[26:29]
	v_mfma_f32_16x16x32_bf16 v[26:29], v[158:161], v[182:185], v[26:29]
	v_mfma_f32_16x16x32_bf16 v[18:21], v[154:157], v[192:195], v[18:21]
	v_mfma_f32_16x16x32_bf16 v[18:21], v[158:161], v[196:199], v[18:21]
	v_mfma_f32_16x16x32_bf16 v[10:13], v[154:157], v[200:203], v[10:13]
	v_mfma_f32_16x16x32_bf16 v[10:13], v[158:161], v[204:207], v[10:13]
	v_mfma_f32_16x16x32_bf16 v[2:5], v[154:157], v[208:211], v[2:5]
	v_mfma_f32_16x16x32_bf16 v[2:5], v[158:161], v[212:215], v[2:5]
	s_setprio 0
	s_barrier
; #define PG8_STAGE(bufoff, gbase, voff) do { const char* gb_ = (const char*)(gbase); asm volatile("" : "+s"(gb_)); _Pragma("unroll") for (int _i = 0; _i < 2; ++_i) { unsigned vo_ = (voff)[_i]; asm volatile("" : "+v"(vo_));        \
;         __builtin_amdgcn_global_load_lds((const unsigned*)(gb_ + vo_), (PG8_LAS unsigned*)(lds + (bufoff) + ldsw + _i * 8192), 16, 0, 0); } } while (0)
; #define PG8_LDA(dst, b, h) do { _Pragma("unroll") for (int m = 0; m < 4; ++m) _Pragma("unroll") for (int k = 0; k < 2; ++k) dst[m][k] = *(const PG8_LAS bf16x8*)(lds + PG8_SA(b, h) + aoff + m * 2048 + k * 1024); } while (0)
; #define PG8_LDB(dst, b, h) do { _Pragma("unroll") for (int n = 0; n < 2; ++n) _Pragma("unroll") for (int k = 0; k < 2; ++k) dst[n][k] = *(const PG8_LAS bf16x8*)(lds + PG8_SB(b, h) + boff + n * 2048 + k * 1024); } while (0)
; #define PG8_MMA(ai, bj, At, Bt) do { __builtin_amdgcn_s_setprio(1); _Pragma("unroll") for (int m = 0; m < 4; ++m) _Pragma("unroll") for (int n = 0; n < 2; ++n) _Pragma("unroll") for (int k = 0; k < 2; ++k) \
;         acc[ai][bj][m][n] = __builtin_amdgcn_mfma_f32_16x16x32_bf16(Bt[n][k], At[m][k], acc[ai][bj][m][n], 0, 0, 0); __builtin_amdgcn_s_setprio(0); } while (0)
; #define PG8_WAIT_V(n) asm volatile("s_waitcnt vmcnt(" #n ")" ::: "memory")
; #define PG8_WAIT_L(n) asm volatile("s_waitcnt lgkmcnt(" #n ")" ::: "memory")
; #define PG8_BAR __builtin_amdgcn_s_barrier()
; #define PG8_SCHED __builtin_amdgcn_sched_barrier(0)
; template <class Epi, class Sched, bool ALIGN_EPI = false, bool SP2 = false>
; __device__ __forceinline__ void gemm_phase(PG8_LAS unsigned char* lds, const Gemm g, const Sched& S, const Epi& E) {
;     ...
;             PG8_LDB(B0, 1, 0); PG8_LDB(B1, 1, 1); PG8_SCHED; PG8_LDA(At, 1, 0); PG8_STAGE(PG8_SA(0, 1), a2 + hstep, voffA);
;             PG8_WAIT_V(8); PG8_WAIT_L(0); PG8_BAR; PG8_MMA(0, 0, At, B0); PG8_MMA(0, 1, At, B1); PG8_BAR; PG8_SCHED;
;             PG8_LDA(At, 1, 1); PG8_STAGE(PG8_SB(1, 0), b3, voffB); PG8_STAGE(PG8_SB(1, 1), b3 + hstep, voffB); PG8_STAGE(PG8_SA(1, 0), a3, voffA);
;             PG8_WAIT_V(8); PG8_WAIT_L(0); PG8_BAR; PG8_MMA(1, 0, At, B0); PG8_MMA(1, 1, At, B1); PG8_BAR; PG8_SCHED;
	s_add_i32 s31, 0, 0x18000
	s_add_i32 s33, 0, 0x1c000
	ds_read_b128 v[74:77], v244 offset:32768
	ds_read_b128 v[78:81], v244 offset:33792
	ds_read_b128 v[82:85], v244 offset:34816
	ds_read_b128 v[146:149], v244 offset:35840
	ds_read_b128 v[150:153], v244 offset:49152
	ds_read_b128 v[154:157], v244 offset:50176
	ds_read_b128 v[158:161], v244 offset:51200
	ds_read_b128 v[178:181], v244 offset:52224
	s_add_u32 s0, s10, 0x80000
	s_addc_u32 s1, s11, 0
	s_mov_b32 m0, s15
	ds_read_b128 v[86:89], v223 offset:32768
	ds_read_b128 v[182:185], v223 offset:33792
	ds_read_b128 v[192:195], v223 offset:34816
	ds_read_b128 v[196:199], v223 offset:35840
	ds_read_b128 v[200:203], v223 offset:36864
	ds_read_b128 v[204:207], v223 offset:37888
	ds_read_b128 v[208:211], v223 offset:38912
	ds_read_b128 v[212:215], v223 offset:39936
	s_nop 0
	global_load_lds_dwordx4 v1, s[0:1]
	s_mov_b32 m0, s16
	s_nop 0
	global_load_lds_dwordx4 v191, s[0:1]
	s_waitcnt vmcnt(8)
	s_waitcnt lgkmcnt(0)
	s_barrier
	s_setprio 1
	s_waitcnt lgkmcnt(0)
	v_mfma_f32_16x16x32_bf16 v[142:145], v[74:77], v[86:89], v[142:145]
	v_mfma_f32_16x16x32_bf16 v[142:145], v[78:81], v[182:185], v[142:145]
	v_mfma_f32_16x16x32_bf16 v[134:137], v[74:77], v[192:195], v[134:137]
	v_mfma_f32_16x16x32_bf16 v[134:137], v[78:81], v[196:199], v[134:137]
	v_mfma_f32_16x16x32_bf16 v[126:129], v[74:77], v[200:203], v[126:129]
	v_mfma_f32_16x16x32_bf16 v[126:129], v[78:81], v[204:207], v[126:129]
	v_mfma_f32_16x16x32_bf16 v[118:121], v[74:77], v[208:211], v[118:121]
	v_mfma_f32_16x16x32_bf16 v[118:121], v[78:81], v[212:215], v[118:121]
	v_mfma_f32_16x16x32_bf16 v[138:141], v[82:85], v[86:89], v[138:141]
	v_mfma_f32_16x16x32_bf16 v[138:141], v[146:149], v[182:185], v[138:141]
	v_mfma_f32_16x16x32_bf16 v[130:133], v[82:85], v[192:195], v[130:133]
	v_mfma_f32_16x16x32_bf16 v[130:133], v[146:149], v[196:199], v[130:133]
	v_mfma_f32_16x16x32_bf16 v[122:125], v[82:85], v[200:203], v[122:125]
	v_mfma_f32_16x16x32_bf16 v[122:125], v[146:149], v[204:207], v[122:125]
	v_mfma_f32_16x16x32_bf16 v[114:117], v[82:85], v[208:211], v[114:117]
	v_mfma_f32_16x16x32_bf16 v[114:117], v[146:149], v[212:215], v[114:117]
	s_setprio 0
	s_setprio 1
	v_mfma_f32_16x16x32_bf16 v[62:65], v[150:153], v[86:89], v[62:65]
	v_mfma_f32_16x16x32_bf16 v[62:65], v[154:157], v[182:185], v[62:65]
	v_mfma_f32_16x16x32_bf16 v[54:57], v[150:153], v[192:195], v[54:57]
	v_mfma_f32_16x16x32_bf16 v[54:57], v[154:157], v[196:199], v[54:57]
	v_mfma_f32_16x16x32_bf16 v[46:49], v[150:153], v[200:203], v[46:49]
	v_mfma_f32_16x16x32_bf16 v[46:49], v[154:157], v[204:207], v[46:49]
	v_mfma_f32_16x16x32_bf16 v[38:41], v[150:153], v[208:211], v[38:41]
	v_mfma_f32_16x16x32_bf16 v[38:41], v[154:157], v[212:215], v[38:41]
	v_mfma_f32_16x16x32_bf16 v[58:61], v[158:161], v[86:89], v[58:61]
	v_mfma_f32_16x16x32_bf16 v[58:61], v[178:181], v[182:185], v[58:61]
	v_mfma_f32_16x16x32_bf16 v[50:53], v[158:161], v[192:195], v[50:53]
	v_mfma_f32_16x16x32_bf16 v[50:53], v[178:181], v[196:199], v[50:53]
	v_mfma_f32_16x16x32_bf16 v[42:45], v[158:161], v[200:203], v[42:45]
	v_mfma_f32_16x16x32_bf16 v[42:45], v[178:181], v[204:207], v[42:45]
	v_mfma_f32_16x16x32_bf16 v[34:37], v[158:161], v[208:211], v[34:37]
	v_mfma_f32_16x16x32_bf16 v[34:37], v[178:181], v[212:215], v[34:37]
	s_setprio 0
	s_barrier
	s_add_u32 s0, s8, 0x80
	s_addc_u32 s1, s9, 0
	s_add_i32 s10, s31, s12
	ds_read_b128 v[182:185], v223 offset:49152
	ds_read_b128 v[192:195], v223 offset:50176
	ds_read_b128 v[196:199], v223 offset:51200
	ds_read_b128 v[200:203], v223 offset:52224
	ds_read_b128 v[204:207], v223 offset:53248
	ds_read_b128 v[208:211], v223 offset:54272
	ds_read_b128 v[212:215], v223 offset:55296
	ds_read_b128 v[224:227], v223 offset:56320
	s_mov_b32 m0, s10
	s_nop 0
	global_load_lds_dwordx4 v189, s[0:1]
	s_add_i32 m0, s10, 0x2000
	s_nop 0
	global_load_lds_dwordx4 v219, s[0:1]
	s_add_u32 s0, s8, 0x80080
	s_addc_u32 s1, s9, 0
	s_add_i32 s8, s33, s12
	s_mov_b32 m0, s8
	s_nop 0
	global_load_lds_dwordx4 v189, s[0:1]
	s_add_i32 m0, s8, 0x2000
	s_nop 0
	global_load_lds_dwordx4 v219, s[0:1]
	s_mov_b32 m0, s19
	s_nop 0
	global_load_lds_dwordx4 v1, s[6:7]
	s_mov_b32 m0, s20
	s_nop 0
	global_load_lds_dwordx4 v191, s[6:7]
	s_waitcnt vmcnt(8)
	s_waitcnt lgkmcnt(0)
	s_barrier
	s_setprio 1
	s_waitcnt lgkmcnt(0)
	v_mfma_f32_16x16x32_bf16 v[86:89], v[74:77], v[182:185], v[110:113]
	v_mfma_f32_16x16x32_bf16 v[110:113], v[78:81], v[192:195], v[86:89]
	v_mfma_f32_16x16x32_bf16 v[66:69], v[74:77], v[212:215], v[66:69]
	v_mfma_f32_16x16x32_bf16 v[86:89], v[82:85], v[182:185], v[106:109]
	v_mfma_f32_16x16x32_bf16 v[106:109], v[146:149], v[192:195], v[86:89]
	v_mfma_f32_16x16x32_bf16 v[86:89], v[74:77], v[196:199], v[102:105]
	v_mfma_f32_16x16x32_bf16 v[102:105], v[78:81], v[200:203], v[86:89]
	v_mfma_f32_16x16x32_bf16 v[86:89], v[82:85], v[196:199], v[98:101]
	v_mfma_f32_16x16x32_bf16 v[98:101], v[146:149], v[200:203], v[86:89]
	v_mfma_f32_16x16x32_bf16 v[86:89], v[74:77], v[204:207], v[94:97]
	v_mfma_f32_16x16x32_bf16 v[94:97], v[78:81], v[208:211], v[86:89]
	v_mfma_f32_16x16x32_bf16 v[86:89], v[82:85], v[204:207], v[90:93]
	v_mfma_f32_16x16x32_bf16 v[90:93], v[146:149], v[208:211], v[86:89]
	v_mfma_f32_16x16x32_bf16 v[86:89], v[78:81], v[224:227], v[66:69]
	v_mfma_f32_16x16x32_bf16 v[66:69], v[82:85], v[212:215], v[70:73]
	v_mfma_f32_16x16x32_bf16 v[82:85], v[146:149], v[224:227], v[66:69]
	s_setprio 0
	s_setprio 1
	v_mfma_f32_16x16x32_bf16 v[30:33], v[150:153], v[182:185], v[30:33]
	v_mfma_f32_16x16x32_bf16 v[30:33], v[154:157], v[192:195], v[30:33]
	v_mfma_f32_16x16x32_bf16 v[22:25], v[150:153], v[196:199], v[22:25]
	v_mfma_f32_16x16x32_bf16 v[22:25], v[154:157], v[200:203], v[22:25]
	v_mfma_f32_16x16x32_bf16 v[14:17], v[150:153], v[204:207], v[14:17]
	v_mfma_f32_16x16x32_bf16 v[14:17], v[154:157], v[208:211], v[14:17]
	v_mfma_f32_16x16x32_bf16 v[6:9], v[150:153], v[212:215], v[6:9]
	v_mfma_f32_16x16x32_bf16 v[6:9], v[154:157], v[224:227], v[6:9]
	v_mfma_f32_16x16x32_bf16 v[26:29], v[158:161], v[182:185], v[26:29]
	v_mfma_f32_16x16x32_bf16 v[26:29], v[178:181], v[192:195], v[26:29]
	v_mfma_f32_16x16x32_bf16 v[18:21], v[158:161], v[196:199], v[18:21]
	v_mfma_f32_16x16x32_bf16 v[18:21], v[178:181], v[200:203], v[18:21]
	v_mfma_f32_16x16x32_bf16 v[10:13], v[158:161], v[204:207], v[10:13]
	v_mfma_f32_16x16x32_bf16 v[10:13], v[178:181], v[208:211], v[10:13]
	v_mfma_f32_16x16x32_bf16 v[2:5], v[158:161], v[212:215], v[2:5]
	v_mfma_f32_16x16x32_bf16 v[2:5], v[178:181], v[224:227], v[2:5]
	s_setprio 0
	s_add_i32 s30, s30, 2
	s_add_u32 s28, s28, 0x100
	s_addc_u32 s29, s29, 0
	s_cmp_gt_u32 s30, 29
	s_mov_b64 s[0:1], s[2:3]
	s_cbranch_scc1 .Lxt_proj
	s_barrier
	s_branch .LBB0_232
.Lxt_proj:
	s_and_b64 vcc, exec, s[44:45]
	s_cbranch_vccz .LBB0_235
	s_barrier

; #define PG8_STAGE(bufoff, gbase, voff) do { const char* gb_ = (const char*)(gbase); asm volatile("" : "+s"(gb_)); _Pragma("unroll") for (int _i = 0; _i < 2; ++_i) { unsigned vo_ = (voff)[_i]; asm volatile("" : "+v"(vo_));        \
;         __builtin_amdgcn_global_load_lds((const unsigned*)(gb_ + vo_), (PG8_LAS unsigned*)(lds + (bufoff) + ldsw + _i * 8192), 16, 0, 0); } } while (0)
; #define PG8_LDA(dst, b, h) do { _Pragma("unroll") for (int m = 0; m < 4; ++m) _Pragma("unroll") for (int k = 0; k < 2; ++k) dst[m][k] = *(const PG8_LAS bf16x8*)(lds + PG8_SA(b, h) + aoff + m * 2048 + k * 1024); } while (0)
; #define PG8_LDB(dst, b, h) do { _Pragma("unroll") for (int n = 0; n < 2; ++n) _Pragma("unroll") for (int k = 0; k < 2; ++k) dst[n][k] = *(const PG8_LAS bf16x8*)(lds + PG8_SB(b, h) + boff + n * 2048 + k * 1024); } while (0)
; #define PG8_MMA(ai, bj, At, Bt) do { __builtin_amdgcn_s_setprio(1); _Pragma("unroll") for (int m = 0; m < 4; ++m) _Pragma("unroll") for (int n = 0; n < 2; ++n) _Pragma("unroll") for (int k = 0; k < 2; ++k) \
;         acc[ai][bj][m][n] = __builtin_amdgcn_mfma_f32_16x16x32_bf16(Bt[n][k], At[m][k], acc[ai][bj][m][n], 0, 0, 0); __builtin_amdgcn_s_setprio(0); } while (0)
; #define PG8_WAIT_V(n) asm volatile("s_waitcnt vmcnt(" #n ")" ::: "memory")
; template <class Epi, class Sched, bool ALIGN_EPI = false, bool SP2 = false>
; __device__ __forceinline__ void gemm_phase(PG8_LAS unsigned char* lds, const Gemm g, const Sched& S, const Epi& E) {
;     ...
;             const bool last = (t == nt - 2);
;             const char* a1 = cA + (size_t)(t + 1) * kstep;
;             const char* a2 = last ? nA : cA + (size_t)(t + 2) * kstep; const char* b2 = last ? nB : cB + (size_t)(t + 2) * kstep;
;             const char* a3 = a2 + kstep; const char* b3 = b2 + kstep;
;             if (last && has_next) S.a_ready(nxt);
;             if constexpr (SP2) {
;             PG8_LDB(B0, 0, 0); PG8_LDB(B1, 0, 1); PG8_SCHED; PG8_LDA(At, 0, 0); PG8_STAGE(PG8_SA(1, 1), a1 + hstep, voffA);
;             PG8_WAIT_V(8); PG8_WAIT_L(0); PG8_BAR; PG8_MMA(0, 0, At, B0); PG8_MMA(0, 1, At, B1); PG8_BAR; PG8_SCHED;
;             PG8_LDA(At, 0, 1); PG8_STAGE(PG8_SB(0, 0), b2, voffB); PG8_STAGE(PG8_SB(0, 1), b2 + hstep, voffB); PG8_STAGE(PG8_SA(0, 0), a2, voffA);
;             PG8_WAIT_V(8); PG8_WAIT_L(0); PG8_BAR; PG8_MMA(1, 0, At, B0); PG8_MMA(1, 1, At, B1); PG8_BAR; PG8_SCHED;
.LBB0_634:
	s_add_u32 s16, s14, 0x100
	s_addc_u32 s17, s15, 0
	s_cmp_eq_u32 s53, 28
	s_cselect_b32 s22, s49, s16
	s_cselect_b32 s23, s7, s17
	s_cselect_b32 s20, s50, s51
	s_cselect_b32 s21, s5, s52
	s_add_u32 s18, s22, 0x80
	s_addc_u32 s19, s23, 0
	s_add_i32 s54, 0, 0x10000
	s_add_i32 s55, 0, 0x14000
	ds_read_b128 v[82:85], v244
	ds_read_b128 v[86:89], v244 offset:1024
	ds_read_b128 v[90:93], v244 offset:2048
	ds_read_b128 v[94:97], v244 offset:3072
	ds_read_b128 v[146:149], v244 offset:16384
	ds_read_b128 v[150:153], v244 offset:17408
	ds_read_b128 v[154:157], v244 offset:18432
	ds_read_b128 v[158:161], v244 offset:19456
	s_add_u32 s14, s14, 0x80080
	s_addc_u32 s15, s15, 0
	ds_read_b128 v[178:181], v188
	ds_read_b128 v[190:193], v188 offset:1024
	ds_read_b128 v[194:197], v188 offset:2048
	ds_read_b128 v[198:201], v188 offset:3072
	ds_read_b128 v[202:205], v188 offset:4096
	ds_read_b128 v[206:209], v188 offset:5120
	ds_read_b128 v[210:213], v188 offset:6144
	ds_read_b128 v[220:223], v188 offset:7168
	s_add_i32 m0, s27, 0xc000
	s_nop 0
	global_load_lds_dwordx4 v1, s[14:15]
	s_add_i32 m0, s27, 0xe000
	s_nop 0
	global_load_lds_dwordx4 v164, s[14:15]
	s_waitcnt vmcnt(8)
	s_waitcnt lgkmcnt(0)
	s_barrier
	s_setprio 1
	s_waitcnt lgkmcnt(0)
	v_mfma_f32_16x16x32_bf16 v[142:145], v[82:85], v[178:181], v[142:145]
	v_mfma_f32_16x16x32_bf16 v[142:145], v[86:89], v[190:193], v[142:145]
	v_mfma_f32_16x16x32_bf16 v[126:129], v[82:85], v[194:197], v[126:129]
	v_mfma_f32_16x16x32_bf16 v[126:129], v[86:89], v[198:201], v[126:129]
	v_mfma_f32_16x16x32_bf16 v[110:113], v[82:85], v[202:205], v[110:113]
	v_mfma_f32_16x16x32_bf16 v[110:113], v[86:89], v[206:209], v[110:113]
	v_mfma_f32_16x16x32_bf16 v[78:81], v[82:85], v[210:213], v[78:81]
	v_mfma_f32_16x16x32_bf16 v[78:81], v[86:89], v[220:223], v[78:81]
	v_mfma_f32_16x16x32_bf16 v[138:141], v[90:93], v[178:181], v[138:141]
	v_mfma_f32_16x16x32_bf16 v[138:141], v[94:97], v[190:193], v[138:141]
	v_mfma_f32_16x16x32_bf16 v[122:125], v[90:93], v[194:197], v[122:125]
	v_mfma_f32_16x16x32_bf16 v[122:125], v[94:97], v[198:201], v[122:125]
	v_mfma_f32_16x16x32_bf16 v[106:109], v[90:93], v[202:205], v[106:109]
	v_mfma_f32_16x16x32_bf16 v[106:109], v[94:97], v[206:209], v[106:109]
	v_mfma_f32_16x16x32_bf16 v[74:77], v[90:93], v[210:213], v[74:77]
	v_mfma_f32_16x16x32_bf16 v[74:77], v[94:97], v[220:223], v[74:77]
	s_setprio 0
	s_setprio 1
	v_mfma_f32_16x16x32_bf16 v[134:137], v[146:149], v[178:181], v[134:137]
	v_mfma_f32_16x16x32_bf16 v[134:137], v[150:153], v[190:193], v[134:137]
	v_mfma_f32_16x16x32_bf16 v[118:121], v[146:149], v[194:197], v[118:121]
	v_mfma_f32_16x16x32_bf16 v[118:121], v[150:153], v[198:201], v[118:121]
	v_mfma_f32_16x16x32_bf16 v[102:105], v[146:149], v[202:205], v[102:105]
	v_mfma_f32_16x16x32_bf16 v[102:105], v[150:153], v[206:209], v[102:105]
	v_mfma_f32_16x16x32_bf16 v[70:73], v[146:149], v[210:213], v[70:73]
	v_mfma_f32_16x16x32_bf16 v[70:73], v[150:153], v[220:223], v[70:73]
	v_mfma_f32_16x16x32_bf16 v[130:133], v[154:157], v[178:181], v[130:133]
	v_mfma_f32_16x16x32_bf16 v[130:133], v[158:161], v[190:193], v[130:133]
	v_mfma_f32_16x16x32_bf16 v[114:117], v[154:157], v[194:197], v[114:117]
	v_mfma_f32_16x16x32_bf16 v[114:117], v[158:161], v[198:201], v[114:117]
	v_mfma_f32_16x16x32_bf16 v[98:101], v[154:157], v[202:205], v[98:101]
	v_mfma_f32_16x16x32_bf16 v[98:101], v[158:161], v[206:209], v[98:101]
	v_mfma_f32_16x16x32_bf16 v[66:69], v[154:157], v[210:213], v[66:69]
	v_mfma_f32_16x16x32_bf16 v[66:69], v[158:161], v[220:223], v[66:69]
	s_setprio 0
	s_barrier
	s_mov_b64 s[14:15], s[20:21]
	s_add_i32 s54, s54, s26
	ds_read_b128 v[178:181], v188 offset:16384
	ds_read_b128 v[190:193], v188 offset:17408
	ds_read_b128 v[194:197], v188 offset:18432
	ds_read_b128 v[198:201], v188 offset:19456
	ds_read_b128 v[202:205], v188 offset:20480
	ds_read_b128 v[206:209], v188 offset:21504
	ds_read_b128 v[210:213], v188 offset:22528
	ds_read_b128 v[220:223], v188 offset:23552
	s_mov_b32 m0, s54
	s_nop 0
	global_load_lds_dwordx4 v162, s[14:15]
	s_add_i32 m0, s54, 0x2000
	s_nop 0
	global_load_lds_dwordx4 v184, s[14:15]
	s_add_u32 s14, s20, 0x80000
	s_addc_u32 s15, s21, 0
	s_add_i32 s54, s55, s26
	s_mov_b32 m0, s54
	s_nop 0
	global_load_lds_dwordx4 v162, s[14:15]
	s_add_i32 m0, s54, 0x2000
	s_nop 0
	global_load_lds_dwordx4 v184, s[14:15]
	s_mov_b64 s[14:15], s[22:23]
	s_mov_b32 m0, s27
	s_nop 0
	global_load_lds_dwordx4 v1, s[14:15]
	s_mov_b32 m0, s28
	s_nop 0
	global_load_lds_dwordx4 v164, s[14:15]
	s_waitcnt vmcnt(8)
	s_waitcnt lgkmcnt(0)
	s_barrier
; #define PG8_STAGE(bufoff, gbase, voff) do { const char* gb_ = (const char*)(gbase); asm volatile("" : "+s"(gb_)); _Pragma("unroll") for (int _i = 0; _i < 2; ++_i) { unsigned vo_ = (voff)[_i]; asm volatile("" : "+v"(vo_));        \
;         __builtin_amdgcn_global_load_lds((const unsigned*)(gb_ + vo_), (PG8_LAS unsigned*)(lds + (bufoff) + ldsw + _i * 8192), 16, 0, 0); } } while (0)
; #define PG8_LDA(dst, b, h) do { _Pragma("unroll") for (int m = 0; m < 4; ++m) _Pragma("unroll") for (int k = 0; k < 2; ++k) dst[m][k] = *(const PG8_LAS bf16x8*)(lds + PG8_SA(b, h) + aoff + m * 2048 + k * 1024); } while (0)
; #define PG8_LDB(dst, b, h) do { _Pragma("unroll") for (int n = 0; n < 2; ++n) _Pragma("unroll") for (int k = 0; k < 2; ++k) dst[n][k] = *(const PG8_LAS bf16x8*)(lds + PG8_SB(b, h) + boff + n * 2048 + k * 1024); } while (0)
; #define PG8_MMA(ai, bj, At, Bt) do { __builtin_amdgcn_s_setprio(1); _Pragma("unroll") for (int m = 0; m < 4; ++m) _Pragma("unroll") for (int n = 0; n < 2; ++n) _Pragma("unroll") for (int k = 0; k < 2; ++k) \
;         acc[ai][bj][m][n] = __builtin_amdgcn_mfma_f32_16x16x32_bf16(Bt[n][k], At[m][k], acc[ai][bj][m][n], 0, 0, 0); __builtin_amdgcn_s_setprio(0); } while (0)
; #define PG8_WAIT_V(n) asm volatile("s_waitcnt vmcnt(" #n ")" ::: "memory")
; #define PG8_WAIT_L(n) asm volatile("s_waitcnt lgkmcnt(" #n ")" ::: "memory")
; #define PG8_BAR __builtin_amdgcn_s_barrier()
; #define PG8_SCHED __builtin_amdgcn_sched_barrier(0)
; template <class Epi, class Sched, bool ALIGN_EPI = false, bool SP2 = false>
; __device__ __forceinline__ void gemm_phase(PG8_LAS unsigned char* lds, const Gemm g, const Sched& S, const Epi& E) {
;     ...
;             PG8_WAIT_V(8); PG8_WAIT_L(0); PG8_BAR; PG8_MMA(1, 0, At, B0); PG8_MMA(1, 1, At, B1); PG8_BAR; PG8_SCHED;
;             PG8_LDB(B0, 1, 0); PG8_LDB(B1, 1, 1); PG8_SCHED; PG8_LDA(At, 1, 0); PG8_STAGE(PG8_SA(0, 1), a2 + hstep, voffA);
;             PG8_WAIT_V(8); PG8_WAIT_L(0); PG8_BAR; PG8_MMA(0, 0, At, B0); PG8_MMA(0, 1, At, B1); PG8_BAR; PG8_SCHED;
	s_setprio 1
	s_waitcnt lgkmcnt(0)
	v_mfma_f32_16x16x32_bf16 v[62:65], v[82:85], v[178:181], v[62:65]
	v_mfma_f32_16x16x32_bf16 v[62:65], v[86:89], v[190:193], v[62:65]
	v_mfma_f32_16x16x32_bf16 v[46:49], v[82:85], v[194:197], v[46:49]
	v_mfma_f32_16x16x32_bf16 v[46:49], v[86:89], v[198:201], v[46:49]
	v_mfma_f32_16x16x32_bf16 v[30:33], v[82:85], v[202:205], v[30:33]
	v_mfma_f32_16x16x32_bf16 v[30:33], v[86:89], v[206:209], v[30:33]
	v_mfma_f32_16x16x32_bf16 v[14:17], v[82:85], v[210:213], v[14:17]
	v_mfma_f32_16x16x32_bf16 v[14:17], v[86:89], v[220:223], v[14:17]
	v_mfma_f32_16x16x32_bf16 v[58:61], v[90:93], v[178:181], v[58:61]
	v_mfma_f32_16x16x32_bf16 v[58:61], v[94:97], v[190:193], v[58:61]
	v_mfma_f32_16x16x32_bf16 v[42:45], v[90:93], v[194:197], v[42:45]
	v_mfma_f32_16x16x32_bf16 v[42:45], v[94:97], v[198:201], v[42:45]
	v_mfma_f32_16x16x32_bf16 v[26:29], v[90:93], v[202:205], v[26:29]
	v_mfma_f32_16x16x32_bf16 v[26:29], v[94:97], v[206:209], v[26:29]
	v_mfma_f32_16x16x32_bf16 v[10:13], v[90:93], v[210:213], v[10:13]
	v_mfma_f32_16x16x32_bf16 v[10:13], v[94:97], v[220:223], v[10:13]
	s_setprio 0
	s_setprio 1
	v_mfma_f32_16x16x32_bf16 v[54:57], v[146:149], v[178:181], v[54:57]
	v_mfma_f32_16x16x32_bf16 v[54:57], v[150:153], v[190:193], v[54:57]
	v_mfma_f32_16x16x32_bf16 v[38:41], v[146:149], v[194:197], v[38:41]
	v_mfma_f32_16x16x32_bf16 v[38:41], v[150:153], v[198:201], v[38:41]
	v_mfma_f32_16x16x32_bf16 v[22:25], v[146:149], v[202:205], v[22:25]
	v_mfma_f32_16x16x32_bf16 v[22:25], v[150:153], v[206:209], v[22:25]
	v_mfma_f32_16x16x32_bf16 v[6:9], v[146:149], v[210:213], v[6:9]
	v_mfma_f32_16x16x32_bf16 v[6:9], v[150:153], v[220:223], v[6:9]
	v_mfma_f32_16x16x32_bf16 v[50:53], v[154:157], v[178:181], v[50:53]
	v_mfma_f32_16x16x32_bf16 v[50:53], v[158:161], v[190:193], v[50:53]
	v_mfma_f32_16x16x32_bf16 v[34:37], v[154:157], v[194:197], v[34:37]
	v_mfma_f32_16x16x32_bf16 v[34:37], v[158:161], v[198:201], v[34:37]
	v_mfma_f32_16x16x32_bf16 v[18:21], v[154:157], v[202:205], v[18:21]
	v_mfma_f32_16x16x32_bf16 v[18:21], v[158:161], v[206:209], v[18:21]
	v_mfma_f32_16x16x32_bf16 v[2:5], v[154:157], v[210:213], v[2:5]
	v_mfma_f32_16x16x32_bf16 v[2:5], v[158:161], v[220:223], v[2:5]
	s_setprio 0
	s_barrier
	s_add_i32 s54, 0, 0x18000
	s_add_i32 s55, 0, 0x1c000
	ds_read_b128 v[82:85], v244 offset:32768
	ds_read_b128 v[86:89], v244 offset:33792
	ds_read_b128 v[90:93], v244 offset:34816
	ds_read_b128 v[94:97], v244 offset:35840
	ds_read_b128 v[146:149], v244 offset:49152
	ds_read_b128 v[150:153], v244 offset:50176
	ds_read_b128 v[154:157], v244 offset:51200
	ds_read_b128 v[158:161], v244 offset:52224
	s_add_u32 s14, s22, 0x80000
	s_addc_u32 s15, s23, 0
	s_mov_b32 m0, s29
	ds_read_b128 v[178:181], v188 offset:32768
	ds_read_b128 v[190:193], v188 offset:33792
	ds_read_b128 v[194:197], v188 offset:34816
	ds_read_b128 v[198:201], v188 offset:35840
	ds_read_b128 v[202:205], v188 offset:36864
	ds_read_b128 v[206:209], v188 offset:37888
	ds_read_b128 v[210:213], v188 offset:38912
	ds_read_b128 v[220:223], v188 offset:39936
	s_nop 0
	global_load_lds_dwordx4 v1, s[14:15]
	s_mov_b32 m0, s33
	s_nop 0
	global_load_lds_dwordx4 v164, s[14:15]
	s_waitcnt vmcnt(8)
	s_waitcnt lgkmcnt(0)
	s_barrier
	s_setprio 1
	s_waitcnt lgkmcnt(0)
	v_mfma_f32_16x16x32_bf16 v[142:145], v[82:85], v[178:181], v[142:145]
	v_mfma_f32_16x16x32_bf16 v[142:145], v[86:89], v[190:193], v[142:145]
	v_mfma_f32_16x16x32_bf16 v[126:129], v[82:85], v[194:197], v[126:129]
	v_mfma_f32_16x16x32_bf16 v[126:129], v[86:89], v[198:201], v[126:129]
	v_mfma_f32_16x16x32_bf16 v[110:113], v[82:85], v[202:205], v[110:113]
	v_mfma_f32_16x16x32_bf16 v[110:113], v[86:89], v[206:209], v[110:113]
	v_mfma_f32_16x16x32_bf16 v[78:81], v[82:85], v[210:213], v[78:81]
	v_mfma_f32_16x16x32_bf16 v[78:81], v[86:89], v[220:223], v[78:81]
	v_mfma_f32_16x16x32_bf16 v[138:141], v[90:93], v[178:181], v[138:141]
	v_mfma_f32_16x16x32_bf16 v[138:141], v[94:97], v[190:193], v[138:141]
	v_mfma_f32_16x16x32_bf16 v[122:125], v[90:93], v[194:197], v[122:125]
	v_mfma_f32_16x16x32_bf16 v[122:125], v[94:97], v[198:201], v[122:125]
	v_mfma_f32_16x16x32_bf16 v[106:109], v[90:93], v[202:205], v[106:109]
	v_mfma_f32_16x16x32_bf16 v[106:109], v[94:97], v[206:209], v[106:109]
	v_mfma_f32_16x16x32_bf16 v[74:77], v[90:93], v[210:213], v[74:77]
	v_mfma_f32_16x16x32_bf16 v[74:77], v[94:97], v[220:223], v[74:77]
	s_setprio 0
	s_setprio 1
	v_mfma_f32_16x16x32_bf16 v[134:137], v[146:149], v[178:181], v[134:137]
	v_mfma_f32_16x16x32_bf16 v[134:137], v[150:153], v[190:193], v[134:137]
	v_mfma_f32_16x16x32_bf16 v[118:121], v[146:149], v[194:197], v[118:121]
	v_mfma_f32_16x16x32_bf16 v[118:121], v[150:153], v[198:201], v[118:121]
	v_mfma_f32_16x16x32_bf16 v[102:105], v[146:149], v[202:205], v[102:105]
	v_mfma_f32_16x16x32_bf16 v[102:105], v[150:153], v[206:209], v[102:105]
	v_mfma_f32_16x16x32_bf16 v[70:73], v[146:149], v[210:213], v[70:73]
	v_mfma_f32_16x16x32_bf16 v[70:73], v[150:153], v[220:223], v[70:73]
	v_mfma_f32_16x16x32_bf16 v[130:133], v[154:157], v[178:181], v[130:133]
	v_mfma_f32_16x16x32_bf16 v[130:133], v[158:161], v[190:193], v[130:133]
	v_mfma_f32_16x16x32_bf16 v[114:117], v[154:157], v[194:197], v[114:117]
	v_mfma_f32_16x16x32_bf16 v[114:117], v[158:161], v[198:201], v[114:117]
	v_mfma_f32_16x16x32_bf16 v[98:101], v[154:157], v[202:205], v[98:101]
	v_mfma_f32_16x16x32_bf16 v[98:101], v[158:161], v[206:209], v[98:101]
	v_mfma_f32_16x16x32_bf16 v[66:69], v[154:157], v[210:213], v[66:69]
	v_mfma_f32_16x16x32_bf16 v[66:69], v[158:161], v[220:223], v[66:69]
	s_setprio 0
	s_barrier
; #define PG8_STAGE(bufoff, gbase, voff) do { const char* gb_ = (const char*)(gbase); asm volatile("" : "+s"(gb_)); _Pragma("unroll") for (int _i = 0; _i < 2; ++_i) { unsigned vo_ = (voff)[_i]; asm volatile("" : "+v"(vo_));        \
;         __builtin_amdgcn_global_load_lds((const unsigned*)(gb_ + vo_), (PG8_LAS unsigned*)(lds + (bufoff) + ldsw + _i * 8192), 16, 0, 0); } } while (0)
; #define PG8_LDA(dst, b, h) do { _Pragma("unroll") for (int m = 0; m < 4; ++m) _Pragma("unroll") for (int k = 0; k < 2; ++k) dst[m][k] = *(const PG8_LAS bf16x8*)(lds + PG8_SA(b, h) + aoff + m * 2048 + k * 1024); } while (0)
; #define PG8_MMA(ai, bj, At, Bt) do { __builtin_amdgcn_s_setprio(1); _Pragma("unroll") for (int m = 0; m < 4; ++m) _Pragma("unroll") for (int n = 0; n < 2; ++n) _Pragma("unroll") for (int k = 0; k < 2; ++k) \
;         acc[ai][bj][m][n] = __builtin_amdgcn_mfma_f32_16x16x32_bf16(Bt[n][k], At[m][k], acc[ai][bj][m][n], 0, 0, 0); __builtin_amdgcn_s_setprio(0); } while (0)
; #define PG8_WAIT_V(n) asm volatile("s_waitcnt vmcnt(" #n ")" ::: "memory")
; #define PG8_WAIT_L(n) asm volatile("s_waitcnt lgkmcnt(" #n ")" ::: "memory")
; #define PG8_BAR __builtin_amdgcn_s_barrier()
; #define PG8_SCHED __builtin_amdgcn_sched_barrier(0)
; template <class Epi, class Sched, bool ALIGN_EPI = false, bool SP2 = false>
; __device__ __forceinline__ void gemm_phase(PG8_LAS unsigned char* lds, const Gemm g, const Sched& S, const Epi& E) {
;     ...
;             PG8_LDA(At, 1, 1); PG8_STAGE(PG8_SB(1, 0), b3, voffB); PG8_STAGE(PG8_SB(1, 1), b3 + hstep, voffB); PG8_STAGE(PG8_SA(1, 0), a3, voffA);
;             PG8_WAIT_V(8); PG8_WAIT_L(0); PG8_BAR; PG8_MMA(1, 0, At, B0); PG8_MMA(1, 1, At, B1); PG8_BAR; PG8_SCHED;
	s_add_u32 s14, s20, 0x80
	s_addc_u32 s15, s21, 0
	s_add_i32 s22, s54, s26
	ds_read_b128 v[178:181], v188 offset:49152
	ds_read_b128 v[190:193], v188 offset:50176
	ds_read_b128 v[194:197], v188 offset:51200
	ds_read_b128 v[198:201], v188 offset:52224
	ds_read_b128 v[202:205], v188 offset:53248
	ds_read_b128 v[206:209], v188 offset:54272
	ds_read_b128 v[210:213], v188 offset:55296
	ds_read_b128 v[220:223], v188 offset:56320
	s_mov_b32 m0, s22
	s_nop 0
	global_load_lds_dwordx4 v162, s[14:15]
	s_add_i32 m0, s22, 0x2000
	s_nop 0
	global_load_lds_dwordx4 v184, s[14:15]
	s_add_u32 s14, s20, 0x80080
	s_addc_u32 s15, s21, 0
	s_add_i32 s20, s55, s26
	s_mov_b32 m0, s20
	s_nop 0
	global_load_lds_dwordx4 v162, s[14:15]
	s_add_i32 m0, s20, 0x2000
	s_nop 0
	global_load_lds_dwordx4 v184, s[14:15]
	s_mov_b32 m0, s38
	s_nop 0
	global_load_lds_dwordx4 v1, s[18:19]
	s_mov_b32 m0, s39
	s_nop 0
	global_load_lds_dwordx4 v164, s[18:19]
	s_waitcnt vmcnt(8)
	s_waitcnt lgkmcnt(0)
	s_barrier
	s_setprio 1
	s_waitcnt lgkmcnt(0)
	v_mfma_f32_16x16x32_bf16 v[62:65], v[82:85], v[178:181], v[62:65]
	v_mfma_f32_16x16x32_bf16 v[62:65], v[86:89], v[190:193], v[62:65]
	v_mfma_f32_16x16x32_bf16 v[46:49], v[82:85], v[194:197], v[46:49]
	v_mfma_f32_16x16x32_bf16 v[46:49], v[86:89], v[198:201], v[46:49]
	v_mfma_f32_16x16x32_bf16 v[30:33], v[82:85], v[202:205], v[30:33]
	v_mfma_f32_16x16x32_bf16 v[30:33], v[86:89], v[206:209], v[30:33]
	v_mfma_f32_16x16x32_bf16 v[14:17], v[82:85], v[210:213], v[14:17]
	v_mfma_f32_16x16x32_bf16 v[14:17], v[86:89], v[220:223], v[14:17]
	v_mfma_f32_16x16x32_bf16 v[58:61], v[90:93], v[178:181], v[58:61]
	v_mfma_f32_16x16x32_bf16 v[58:61], v[94:97], v[190:193], v[58:61]
	v_mfma_f32_16x16x32_bf16 v[42:45], v[90:93], v[194:197], v[42:45]
	v_mfma_f32_16x16x32_bf16 v[42:45], v[94:97], v[198:201], v[42:45]
	v_mfma_f32_16x16x32_bf16 v[26:29], v[90:93], v[202:205], v[26:29]
	v_mfma_f32_16x16x32_bf16 v[26:29], v[94:97], v[206:209], v[26:29]
	v_mfma_f32_16x16x32_bf16 v[10:13], v[90:93], v[210:213], v[10:13]
	v_mfma_f32_16x16x32_bf16 v[10:13], v[94:97], v[220:223], v[10:13]
	s_setprio 0
	s_setprio 1
	v_mfma_f32_16x16x32_bf16 v[54:57], v[146:149], v[178:181], v[54:57]
	v_mfma_f32_16x16x32_bf16 v[54:57], v[150:153], v[190:193], v[54:57]
	v_mfma_f32_16x16x32_bf16 v[38:41], v[146:149], v[194:197], v[38:41]
	v_mfma_f32_16x16x32_bf16 v[38:41], v[150:153], v[198:201], v[38:41]
	v_mfma_f32_16x16x32_bf16 v[22:25], v[146:149], v[202:205], v[22:25]
	v_mfma_f32_16x16x32_bf16 v[22:25], v[150:153], v[206:209], v[22:25]
	v_mfma_f32_16x16x32_bf16 v[6:9], v[146:149], v[210:213], v[6:9]
	v_mfma_f32_16x16x32_bf16 v[6:9], v[150:153], v[220:223], v[6:9]
	v_mfma_f32_16x16x32_bf16 v[50:53], v[154:157], v[178:181], v[50:53]
	v_mfma_f32_16x16x32_bf16 v[50:53], v[158:161], v[190:193], v[50:53]
	v_mfma_f32_16x16x32_bf16 v[34:37], v[154:157], v[194:197], v[34:37]
	v_mfma_f32_16x16x32_bf16 v[34:37], v[158:161], v[198:201], v[34:37]
	v_mfma_f32_16x16x32_bf16 v[18:21], v[154:157], v[202:205], v[18:21]
	v_mfma_f32_16x16x32_bf16 v[18:21], v[158:161], v[206:209], v[18:21]
	v_mfma_f32_16x16x32_bf16 v[2:5], v[154:157], v[210:213], v[2:5]
	v_mfma_f32_16x16x32_bf16 v[2:5], v[158:161], v[220:223], v[2:5]
	s_setprio 0
	s_add_i32 s53, s53, 2
	s_add_u32 s51, s51, 0x100
	s_addc_u32 s52, s52, 0
	s_cmp_gt_u32 s53, 29
	s_mov_b64 s[14:15], s[16:17]
	s_cbranch_scc1 .Lxt_ffi
	s_barrier
	s_branch .LBB0_634
.Lxt_ffi:
	s_and_b64 vcc, exec, s[2:3]
	s_cbranch_vccz .LBB0_637
	s_barrier
